# attention sel loop: per-step wave-uniform tile-selected test done with s_bitcmp1_b64 on a per-item OR-reduced selection mask instead of 6 VALU + vcc branch
# speedup vs baseline: 1.0037x; 1.0037x over previous
.LBB0_1147:
	v_lshlrev_b32_e32 v34, 12, v225
	v_add3_u32 v109, s77, v34, v38
	v_lshl_add_u32 v34, v226, 3, 0
	v_add_u32_e32 v34, 0x20000, v34
	v_pk_mul_f32 v[2:3], v[0:1], v[2:3] op_sel_hi:[0,1]
	s_waitcnt lgkmcnt(0)
	s_barrier
	ds_read_b64 v[102:103], v34
	v_cvt_pk_bf16_f32 v34, v2, v3
	v_pk_mul_f32 v[2:3], v[0:1], v[18:19] op_sel_hi:[0,1]
	v_cvt_pk_bf16_f32 v18, v2, v3
	v_pk_mul_f32 v[2:3], v[0:1], v[4:5] op_sel_hi:[0,1]
	v_cvt_pk_bf16_f32 v2, v2, v3
	ds_write2st64_b32 v109, v34, v2 offset1:1
	v_pk_mul_f32 v[2:3], v[0:1], v[20:21] op_sel_hi:[0,1]
	v_cvt_pk_bf16_f32 v2, v2, v3
	ds_write2st64_b32 v109, v18, v2 offset0:8 offset1:9
	v_pk_mul_f32 v[2:3], v[0:1], v[6:7] op_sel_hi:[0,1]
	v_cvt_pk_bf16_f32 v4, v2, v3
	v_pk_mul_f32 v[2:3], v[0:1], v[22:23] op_sel_hi:[0,1]
	v_cvt_pk_bf16_f32 v5, v2, v3
	v_pk_mul_f32 v[2:3], v[0:1], v[8:9] op_sel_hi:[0,1]
	v_cvt_pk_bf16_f32 v2, v2, v3
	ds_write2st64_b32 v109, v4, v2 offset0:2 offset1:3
	v_pk_mul_f32 v[2:3], v[0:1], v[24:25] op_sel_hi:[0,1]
	v_cvt_pk_bf16_f32 v2, v2, v3
	ds_write2st64_b32 v109, v5, v2 offset0:10 offset1:11
	v_pk_mul_f32 v[2:3], v[0:1], v[10:11] op_sel_hi:[0,1]
	v_cvt_pk_bf16_f32 v4, v2, v3
	v_pk_mul_f32 v[2:3], v[0:1], v[26:27] op_sel_hi:[0,1]
	v_cvt_pk_bf16_f32 v5, v2, v3
	v_pk_mul_f32 v[2:3], v[0:1], v[12:13] op_sel_hi:[0,1]
	v_cvt_pk_bf16_f32 v2, v2, v3
	ds_write2st64_b32 v109, v4, v2 offset0:4 offset1:5
	v_pk_mul_f32 v[2:3], v[0:1], v[28:29] op_sel_hi:[0,1]
	s_lshl_b32 s0, s64, 19
	v_readlane_b32 s4, v252, 7
	v_cvt_pk_bf16_f32 v2, v2, v3
	v_readlane_b32 s5, v252, 8
	s_add_u32 s0, s4, s0
	ds_write2st64_b32 v109, v5, v2 offset0:12 offset1:13
	v_pk_mul_f32 v[2:3], v[0:1], v[14:15] op_sel_hi:[0,1]
	s_addc_u32 s1, s5, 0
	v_cvt_pk_bf16_f32 v4, v2, v3
	v_pk_mul_f32 v[2:3], v[0:1], v[30:31] op_sel_hi:[0,1]
	v_lshl_add_u64 v[98:99], v[186:187], 1, s[0:1]
	v_lshl_add_u64 v[100:101], v[188:189], 1, s[0:1]
	s_mov_b64 s[0:1], 0x1800000
	v_cvt_pk_bf16_f32 v5, v2, v3
	v_pk_mul_f32 v[2:3], v[0:1], v[16:17] op_sel_hi:[0,1]
	v_lshl_add_u64 v[106:107], v[100:101], 0, s[0:1]
	s_min_i32 s0, s68, 0
	v_cvt_pk_bf16_f32 v2, v2, v3
	s_mov_b64 s[2:3], 0x1000000
	s_ashr_i32 s1, s0, 31
	ds_write2st64_b32 v109, v4, v2 offset0:6 offset1:7
	v_pk_mul_f32 v[2:3], v[0:1], v[32:33] op_sel_hi:[0,1]
	v_lshl_add_u64 v[104:105], v[98:99], 0, s[2:3]
	s_lshl_b64 s[0:1], s[0:1], 13
	v_readfirstlane_b32 s2, v200
	v_cvt_pk_bf16_f32 v0, v2, v3
	v_lshl_add_u64 v[2:3], v[104:105], 0, s[0:1]
	s_mov_b32 m0, s2
	ds_write2st64_b32 v109, v5, v0 offset0:14 offset1:15
	global_load_lds_dwordx4 v[2:3], off
	v_lshl_add_u64 v[2:3], v[106:107], 0, s[0:1]
	v_readfirstlane_b32 s0, v213
	s_mov_b32 m0, s0
	s_min_i32 s0, s68, 1
	s_ashr_i32 s1, s0, 31
	s_lshl_b64 s[0:1], s[0:1], 13
	v_readfirstlane_b32 s2, v214
	global_load_lds_dwordx4 v[2:3], off
	v_lshl_add_u64 v[2:3], v[104:105], 0, s[0:1]
	s_mov_b32 m0, s2
	v_readfirstlane_b32 s2, v216
	global_load_lds_dwordx4 v[2:3], off
	v_lshl_add_u64 v[2:3], v[106:107], 0, s[0:1]
	v_readfirstlane_b32 s0, v215
	s_mov_b32 m0, s0
	s_min_i32 s0, s68, 2
	s_ashr_i32 s1, s0, 31
	s_lshl_b64 s[0:1], s[0:1], 13
	global_load_lds_dwordx4 v[2:3], off
	v_lshl_add_u64 v[2:3], v[104:105], 0, s[0:1]
	s_mov_b32 m0, s2
	v_readfirstlane_b32 s2, v218
	global_load_lds_dwordx4 v[2:3], off
	v_lshl_add_u64 v[2:3], v[106:107], 0, s[0:1]
	v_readfirstlane_b32 s0, v217
	s_mov_b32 m0, s0
	s_min_i32 s0, s68, 3
	s_ashr_i32 s1, s0, 31
	s_lshl_b64 s[0:1], s[0:1], 13
	global_load_lds_dwordx4 v[2:3], off
	v_lshl_add_u64 v[2:3], v[104:105], 0, s[0:1]
	s_mov_b32 m0, s2
	v_add_u32_e32 v113, s76, v224
	global_load_lds_dwordx4 v[2:3], off
	v_lshl_add_u64 v[2:3], v[106:107], 0, s[0:1]
	v_readfirstlane_b32 s0, v221
	s_mov_b32 m0, s0
	s_min_i32 s0, s68, 4
	s_ashr_i32 s1, s0, 31
	s_lshl_b64 s[0:1], s[0:1], 13
	v_readfirstlane_b32 s2, v113
	global_load_lds_dwordx4 v[2:3], off
	v_lshl_add_u64 v[2:3], v[104:105], 0, s[0:1]
	s_mov_b32 m0, s2
	v_add_u32_e32 v114, s78, v224
	global_load_lds_dwordx4 v[2:3], off
	v_lshl_add_u64 v[2:3], v[106:107], 0, s[0:1]
	v_readfirstlane_b32 s0, v114
	s_mov_b32 m0, s0
	v_lshlrev_b32_e32 v0, 8, v199
	global_load_lds_dwordx4 v[2:3], off
	s_waitcnt vmcnt(8)
	s_barrier
	ds_read_b128 v[2:5], v222
	ds_read_b128 v[6:9], v222 offset:4096
	s_waitcnt lgkmcnt(0)
	v_mfma_f32_32x32x16_bf16 v[34:49], v[2:5], v[162:165], 0
	s_mov_b32 s42, 0
	s_cmp_lt_i32 s74, 64
	s_nop 4
	v_mfma_f32_32x32x16_bf16 v[50:65], v[6:9], v[162:165], 0
	ds_read_b128 v[2:5], v219
	ds_read_b128 v[6:9], v219 offset:4096
	s_nop 0
	v_readlane_b32 s12, v252, 15
	v_readlane_b32 s13, v252, 16
	s_nop 1
	v_readlane_b32 s16, v252, 19
	s_waitcnt lgkmcnt(0)
	v_mfma_f32_32x32x16_bf16 v[34:49], v[2:5], v[166:169], v[34:49]
	v_readlane_b32 s17, v252, 20
	v_readlane_b32 s18, v252, 21
	v_readlane_b32 s19, v252, 22
	v_mfma_f32_32x32x16_bf16 v[50:65], v[6:9], v[166:169], v[50:65]
	ds_read_b128 v[2:5], v212
	ds_read_b128 v[6:9], v212 offset:4096
	s_waitcnt lgkmcnt(0)
	v_mfma_f32_32x32x16_bf16 v[34:49], v[2:5], v[170:173], v[34:49]
	v_mfma_f32_32x32x16_bf16 v[50:65], v[6:9], v[170:173], v[50:65]
	ds_read_b128 v[2:5], v211
	ds_read_b128 v[6:9], v211 offset:4096
	s_waitcnt lgkmcnt(0)
	v_mfma_f32_32x32x16_bf16 v[34:49], v[2:5], v[174:177], v[34:49]
	v_and_b32_e32 v2, 0xc0, v224
	v_add3_u32 v0, 0, v0, v2
	v_add3_u32 v112, v0, v229, v228
	v_mfma_f32_32x32x16_bf16 v[50:65], v[6:9], v[174:177], v[50:65]
	s_cbranch_scc0 .LBB0_1176
	v_mov_b32_e32 v2, v1
	v_mov_b32_e32 v3, v1
	v_mov_b32_e32 v4, v1
	v_mov_b32_e32 v5, v1
	v_mov_b32_e32 v6, v1
	v_mov_b32_e32 v7, v1
	v_mov_b32_e32 v8, v1
	v_mov_b32_e32 v9, v1
	v_mov_b32_e32 v10, v1
	v_mov_b32_e32 v11, v1
	v_mov_b32_e32 v12, v1
	v_mov_b32_e32 v13, v1
	v_mov_b32_e32 v14, v1
	v_mov_b32_e32 v15, v1
	v_mov_b32_e32 v16, v1
	v_mov_b32_e32 v17, v1
	v_mov_b32_e32 v18, v1
	v_mov_b32_e32 v19, v1
	v_mov_b32_e32 v20, v1
	v_mov_b32_e32 v21, v1
	v_mov_b32_e32 v22, v1
	v_mov_b32_e32 v23, v1
	v_mov_b32_e32 v24, v1
	v_mov_b32_e32 v25, v1
	v_mov_b32_e32 v26, v1
	v_mov_b32_e32 v27, v1
	v_mov_b32_e32 v28, v1
	v_mov_b32_e32 v29, v1
	v_mov_b32_e32 v30, v1
	v_mov_b32_e32 v31, v1
	v_mov_b32_e32 v0, v1
	v_mov_b64_e32 v[32:33], v[30:31]
	v_cmp_gt_i32_e64 s[0:1], 0, v184
	s_mov_b32 s43, 5
	s_mov_b64 s[38:39], -1
	v_mov_b32_e32 v115, 0
	v_mov_b32_e32 v116, 0xf149f2ca
	s_movk_i32 s44, 0x7f
	v_mov_b64_e32 v[30:31], v[28:29]
	v_mov_b64_e32 v[28:29], v[26:27]
	v_mov_b64_e32 v[26:27], v[24:25]
	v_mov_b64_e32 v[24:25], v[22:23]
	v_mov_b64_e32 v[22:23], v[20:21]
	v_mov_b64_e32 v[20:21], v[18:19]
	v_mov_b64_e32 v[18:19], v[16:17]
	v_mov_b64_e32 v[16:17], v[14:15]
	v_mov_b64_e32 v[14:15], v[12:13]
	v_mov_b64_e32 v[12:13], v[10:11]
	v_mov_b64_e32 v[10:11], v[8:9]
	v_mov_b64_e32 v[8:9], v[6:7]
	v_mov_b64_e32 v[6:7], v[4:5]
	v_mov_b64_e32 v[4:5], v[2:3]
	v_mov_b64_e32 v[2:3], v[0:1]
	s_mov_b32 s45, 0
	s_waitcnt lgkmcnt(0)
	v_mov_b32_e32 v238, v102
	v_mov_b32_e32 v239, v103
	s_nop 1
	v_or_b32_dpp v238, v238, v238 quad_perm:[1,0,3,2] row_mask:0xf bank_mask:0xf
	v_or_b32_dpp v239, v239, v239 quad_perm:[1,0,3,2] row_mask:0xf bank_mask:0xf
	s_nop 1
	v_or_b32_dpp v238, v238, v238 quad_perm:[2,3,0,1] row_mask:0xf bank_mask:0xf
	v_or_b32_dpp v239, v239, v239 quad_perm:[2,3,0,1] row_mask:0xf bank_mask:0xf
	s_nop 1
	v_or_b32_dpp v238, v238, v238 row_half_mirror row_mask:0xf bank_mask:0xf
	v_or_b32_dpp v239, v239, v239 row_half_mirror row_mask:0xf bank_mask:0xf
	s_nop 1
	v_or_b32_dpp v238, v238, v238 row_mirror row_mask:0xf bank_mask:0xf
	v_or_b32_dpp v239, v239, v239 row_mirror row_mask:0xf bank_mask:0xf
	s_nop 1
	v_readlane_b32 s100, v238, 0
	v_readlane_b32 s98, v238, 16
	v_readlane_b32 s99, v238, 32
	v_readlane_b32 s101, v238, 48
	s_or_b32 s100, s100, s98
	s_or_b32 s99, s99, s101
	s_or_b32 s100, s100, s99
	v_readlane_b32 s101, v239, 0
	v_readlane_b32 s98, v239, 16
	v_readlane_b32 s99, v239, 32
	s_or_b32 s101, s101, s98
	v_readlane_b32 s98, v239, 48
	s_or_b32 s101, s101, s99
	s_or_b32 s101, s101, s98
	s_branch .LBB0_1150

.LBB0_1150:
	s_add_i32 s2, s42, 5
	s_min_i32 s72, s2, s68
	v_lshl_add_u32 v0, s43, 14, v200
	s_lshl_b64 s[2:3], s[72:73], 13
	v_readfirstlane_b32 s4, v0
	v_lshl_add_u64 v[110:111], v[104:105], 0, s[2:3]
	s_mov_b32 m0, s4
	v_add_u32_e32 v0, 0x2000, v0
	s_waitcnt vmcnt(6)
	s_barrier
	global_load_lds_dwordx4 v[110:111], off
	v_lshl_add_u64 v[110:111], v[106:107], 0, s[2:3]
	v_readfirstlane_b32 s2, v0
	s_mov_b32 m0, s2
	s_add_i32 s2, s45, 1
	global_load_lds_dwordx4 v[110:111], off
	s_cmp_lg_u32 s45, 5
	s_cselect_b32 s46, s2, 0
	s_cmp_lt_i32 s42, s68
	s_cselect_b64 s[40:41], -1, 0
	s_cmp_ge_i32 s42, s68
	s_mov_b64 s[10:11], 0
	s_cbranch_scc1 .LBB0_1153
	s_add_i32 s2, s42, 1
	s_bitcmp1_b64 s[100:101], s2
	s_cbranch_scc0 .LBB0_1153
	v_lshl_add_u32 v0, s46, 14, v205
	v_add_u32_e32 v70, v0, v201
	ds_read_b128 v[66:69], v70
	ds_read_b128 v[82:85], v70 offset:4096
	v_add_u32_e32 v108, v0, v202
	ds_read_b128 v[118:121], v108
	ds_read_b128 v[122:125], v108 offset:4096
	v_add_u32_e32 v108, v0, v203
	ds_read_b128 v[126:129], v108
	ds_read_b128 v[130:133], v108 offset:4096
	v_add_u32_e32 v0, v0, v204
	ds_read_b128 v[134:137], v0
	ds_read_b128 v[138:141], v0 offset:4096
	s_mov_b64 s[10:11], -1
	s_waitcnt lgkmcnt(6)
	v_mfma_f32_32x32x16_bf16 v[66:81], v[66:69], v[162:165], 0
	v_mfma_f32_32x32x16_bf16 v[82:97], v[82:85], v[162:165], 0
	s_waitcnt lgkmcnt(4)
	v_mfma_f32_32x32x16_bf16 v[66:81], v[118:121], v[166:169], v[66:81]
	v_mfma_f32_32x32x16_bf16 v[82:97], v[122:125], v[166:169], v[82:97]
	s_waitcnt lgkmcnt(2)
	v_mfma_f32_32x32x16_bf16 v[66:81], v[126:129], v[170:173], v[66:81]
	v_mfma_f32_32x32x16_bf16 v[82:97], v[130:133], v[170:173], v[82:97]
	s_waitcnt lgkmcnt(0)
	v_mfma_f32_32x32x16_bf16 v[66:81], v[134:137], v[174:177], v[66:81]
	v_mfma_f32_32x32x16_bf16 v[82:97], v[138:141], v[174:177], v[82:97]

.LBB0_1162:
	s_add_i32 s2, s43, 1
	s_cmp_lg_u32 s43, 5
	s_cselect_b32 s43, s2, 0
	s_andn2_b64 vcc, exec, s[40:41]
	s_cbranch_vccnz .LBB0_1149
	s_add_i32 s2, s42, 6
	s_min_i32 s72, s2, s68
	v_lshl_add_u32 v0, s43, 14, v200
	s_lshl_b64 s[2:3], s[72:73], 13
	v_readfirstlane_b32 s4, v0
	v_lshl_add_u64 v[110:111], v[104:105], 0, s[2:3]
	s_mov_b32 m0, s4
	v_add_u32_e32 v0, 0x2000, v0
	s_waitcnt vmcnt(6)
	s_barrier
	global_load_lds_dwordx4 v[110:111], off
	v_lshl_add_u64 v[110:111], v[106:107], 0, s[2:3]
	v_readfirstlane_b32 s2, v0
	s_mov_b32 m0, s2
	s_add_i32 s40, s42, 1
	global_load_lds_dwordx4 v[110:111], off
	s_add_i32 s2, s46, 1
	s_cmp_lg_u32 s46, 5
	s_cselect_b32 s45, s2, 0
	s_cmp_ge_i32 s40, s68
	s_mov_b64 s[38:39], 0
	s_cbranch_scc1 .LBB0_1166
	s_add_i32 s2, s42, 2
	s_bitcmp1_b64 s[100:101], s2
	s_cbranch_scc0 .LBB0_1166
	v_lshl_add_u32 v0, s45, 14, v205
	v_add_u32_e32 v38, v0, v201
	ds_read_b128 v[34:37], v38
	ds_read_b128 v[50:53], v38 offset:4096
	v_add_u32_e32 v108, v0, v202
	ds_read_b128 v[118:121], v108
	ds_read_b128 v[122:125], v108 offset:4096
	v_add_u32_e32 v108, v0, v203
	ds_read_b128 v[126:129], v108
	ds_read_b128 v[130:133], v108 offset:4096
	v_add_u32_e32 v0, v0, v204
	ds_read_b128 v[134:137], v0
	ds_read_b128 v[138:141], v0 offset:4096
	s_mov_b64 s[38:39], -1
	s_waitcnt lgkmcnt(6)
	v_mfma_f32_32x32x16_bf16 v[34:49], v[34:37], v[162:165], 0
	v_mfma_f32_32x32x16_bf16 v[50:65], v[50:53], v[162:165], 0
	s_waitcnt lgkmcnt(4)
	v_mfma_f32_32x32x16_bf16 v[34:49], v[118:121], v[166:169], v[34:49]
	v_mfma_f32_32x32x16_bf16 v[50:65], v[122:125], v[166:169], v[50:65]
	s_waitcnt lgkmcnt(2)
	v_mfma_f32_32x32x16_bf16 v[34:49], v[126:129], v[170:173], v[34:49]
	v_mfma_f32_32x32x16_bf16 v[50:65], v[130:133], v[170:173], v[50:65]
	s_waitcnt lgkmcnt(0)
	v_mfma_f32_32x32x16_bf16 v[34:49], v[134:137], v[174:177], v[34:49]
	v_mfma_f32_32x32x16_bf16 v[50:65], v[138:141], v[174:177], v[50:65]

	.amdhsa_kernel _Z18nsa_pool_block_fwd6Params
		.amdhsa_group_segment_fixed_size 0
		.amdhsa_private_segment_fixed_size 0
		.amdhsa_kernarg_size 624
		.amdhsa_user_sgpr_count 2
		.amdhsa_user_sgpr_dispatch_ptr 0
		.amdhsa_user_sgpr_queue_ptr 0
		.amdhsa_user_sgpr_kernarg_segment_ptr 1
		.amdhsa_user_sgpr_dispatch_id 0
		.amdhsa_user_sgpr_kernarg_preload_length 0
		.amdhsa_user_sgpr_kernarg_preload_offset 0
		.amdhsa_user_sgpr_private_segment_size 0
		.amdhsa_uses_dynamic_stack 0
		.amdhsa_enable_private_segment 0
		.amdhsa_system_sgpr_workgroup_id_x 1
		.amdhsa_system_sgpr_workgroup_id_y 0
		.amdhsa_system_sgpr_workgroup_id_z 0
		.amdhsa_system_sgpr_workgroup_info 0
		.amdhsa_system_vgpr_workitem_id 2
		.amdhsa_next_free_vgpr 254
		.amdhsa_next_free_sgpr 102
		.amdhsa_accum_offset 256
		.amdhsa_reserve_vcc 1
		.amdhsa_float_round_mode_32 0
		.amdhsa_float_round_mode_16_64 0
		.amdhsa_float_denorm_mode_32 3
		.amdhsa_float_denorm_mode_16_64 3
		.amdhsa_dx10_clamp 1
		.amdhsa_ieee_mode 1
		.amdhsa_fp16_overflow 0
		.amdhsa_tg_split 0
		.amdhsa_exception_fp_ieee_invalid_op 0
		.amdhsa_exception_fp_denorm_src 0
		.amdhsa_exception_fp_ieee_div_zero 0
		.amdhsa_exception_fp_ieee_overflow 0
		.amdhsa_exception_fp_ieee_underflow 0
		.amdhsa_exception_fp_ieee_inexact 0
		.amdhsa_exception_int_div_zero 0
	.end_amdhsa_kernel

amdhsa.kernels:
  - .agpr_count:     0
    .args:
      - .offset:         0
        .size:           368
        .value_kind:     by_value
      - .offset:         368
        .size:           4
        .value_kind:     hidden_block_count_x
      - .offset:         372
        .size:           4
        .value_kind:     hidden_block_count_y
      - .offset:         376
        .size:           4
        .value_kind:     hidden_block_count_z
      - .offset:         380
        .size:           2
        .value_kind:     hidden_group_size_x
      - .offset:         382
        .size:           2
        .value_kind:     hidden_group_size_y
      - .offset:         384
        .size:           2
        .value_kind:     hidden_group_size_z
      - .offset:         386
        .size:           2
        .value_kind:     hidden_remainder_x
      - .offset:         388
        .size:           2
        .value_kind:     hidden_remainder_y
      - .offset:         390
        .size:           2
        .value_kind:     hidden_remainder_z
      - .offset:         408
        .size:           8
        .value_kind:     hidden_global_offset_x
      - .offset:         416
        .size:           8
        .value_kind:     hidden_global_offset_y
      - .offset:         424
        .size:           8
        .value_kind:     hidden_global_offset_z
      - .offset:         432
        .size:           2
        .value_kind:     hidden_grid_dims
      - .offset:         456
        .size:           8
        .value_kind:     hidden_multigrid_sync_arg
      - .offset:         488
        .size:           4
        .value_kind:     hidden_dynamic_lds_size
    .group_segment_fixed_size: 0
    .kernarg_segment_align: 8
    .kernarg_segment_size: 624
    .language:       OpenCL C
    .language_version:
      - 2
      - 0
    .max_flat_workgroup_size: 512
    .name:           _Z18nsa_pool_block_fwd6Params
    .private_segment_fixed_size: 0
    .sgpr_count:     108
    .sgpr_spill_count: 123
    .symbol:         _Z18nsa_pool_block_fwd6Params.kd
    .uniform_work_group_size: 1
    .uses_dynamic_stack: false
    .vgpr_count:     254
    .vgpr_spill_count: 0
    .wavefront_size: 64
